# retention scan: specialised step loop for part 0 (no output reload / select / add, recounted waits)
# baseline (speedup 1.0000x reference)
.LBB0_525:
	s_or_b64 exec, exec, s[6:7]
	s_add_u32 s8, s12, 0x4400000
	s_addc_u32 s9, s13, 0
	s_add_u32 s10, s12, 0xc700000
	s_addc_u32 s11, s13, 0
	v_and_b32_e32 v21, 15, v18
	s_add_u32 s12, s12, 0xe800000
	v_ashrrev_i32_e32 v19, 4, v18
	v_lshlrev_b32_e32 v0, 3, v21
	s_addc_u32 s13, s13, 0
	s_add_i32 s0, 0, 0x17800
	v_lshl_or_b32 v24, v19, 7, v0
	v_mov_b32_e32 v0, s0
	s_waitcnt lgkmcnt(0)
	s_barrier
	ds_read_b32 v0, v0
	v_mov_b32_e32 v23, s48
	ds_read_b64 v[26:27], v23
	s_lshl_b32 s6, s20, 2
	s_lshl_b32 s19, s21, 9
	s_waitcnt lgkmcnt(1)
	v_readfirstlane_b32 s0, v0
	s_ashr_i32 s0, s0, 7
	s_and_b32 s22, s6, 0x1e0
	s_lshl_b32 s18, s15, 19
	s_ashr_i32 s1, s0, 31
	s_or_b32 s15, s22, s19
	s_lshl_b64 s[6:7], s[0:1], 19
	s_lshl_b32 s94, s15, 8
	s_add_u32 s6, s12, s6
	v_ashrrev_i32_e32 v22, 6, v18
	s_addc_u32 s7, s13, s7
	s_add_u32 s6, s6, s94
	v_ashrrev_i32_e32 v23, 31, v22
	s_addc_u32 s7, s7, 0
	s_lshl_b32 s16, s21, 15
	s_mov_b32 s17, s95
	v_lshlrev_b64 v[28:29], 12, v[22:23]
	s_lshl_b64 s[0:1], s[0:1], 17
	v_lshl_add_u64 v[132:133], v[28:29], 0, s[16:17]
	v_lshl_add_u64 v[28:29], s[0:1], 0, v[132:133]
	v_and_b32_e32 v34, 63, v18
	v_lshlrev_b64 v[28:29], 1, v[28:29]
	v_ashrrev_i32_e32 v25, 31, v24
	v_lshl_add_u64 v[30:31], s[8:9], 0, v[28:29]
	v_lshlrev_b64 v[24:25], 1, v[24:25]
	v_lshlrev_b32_e32 v0, 4, v34
	v_lshl_add_u64 v[32:33], s[6:7], 0, v[24:25]
	v_lshl_add_u64 v[30:31], v[30:31], 0, v[0:1]
	global_load_dwordx4 v[126:129], v[32:33], off
	global_load_dwordx4 v[50:53], v[30:31], off
	global_load_dwordx4 v[54:57], v[30:31], off offset:1024
	global_load_dwordx4 v[58:61], v[30:31], off offset:2048
	v_add_co_u32_e32 v32, vcc, s46, v30
	v_lshl_add_u64 v[28:29], s[10:11], 0, v[28:29]
	s_nop 0
	v_addc_co_u32_e32 v33, vcc, 0, v31, vcc
	v_lshl_add_u64 v[28:29], v[28:29], 0, v[0:1]
	global_load_dwordx4 v[62:65], v[30:31], off offset:3072
	global_load_dwordx4 v[66:69], v[32:33], off
	global_load_dwordx4 v[70:73], v[32:33], off offset:1024
	global_load_dwordx4 v[74:77], v[32:33], off offset:2048
	v_add_co_u32_e32 v30, vcc, s46, v28
	global_load_dwordx4 v[82:85], v[32:33], off offset:3072
	global_load_dwordx4 v[102:105], v[28:29], off
	global_load_dwordx4 v[106:109], v[28:29], off offset:1024
	global_load_dwordx4 v[98:101], v[28:29], off offset:2048
	v_addc_co_u32_e32 v31, vcc, 0, v29, vcc
	global_load_dwordx4 v[110:113], v[28:29], off offset:3072
	global_load_dwordx4 v[114:117], v[30:31], off
	global_load_dwordx4 v[118:121], v[30:31], off offset:1024
	global_load_dwordx4 v[122:125], v[30:31], off offset:2048
	global_load_dwordx4 v[86:89], v[30:31], off offset:3072
	v_mul_f32_e32 v20, 0xc3000000, v20
	v_mul_f32_e32 v20, 0x3fb8aa3b, v20
	v_exp_f32_e32 v134, v20
	v_lshrrev_b32_e32 v20, 2, v18
	v_and_b32_e32 v20, 12, v20
	s_waitcnt lgkmcnt(0)
	v_readfirstlane_b32 s6, v26
	v_lshlrev_b32_e32 v26, 11, v20
	v_lshl_or_b32 v22, v22, 15, v26
	v_and_b32_e32 v28, 31, v18
	v_or3_b32 v22, v22, v21, s19
	v_mul_lo_u32 v19, v19, s66
	s_add_i32 s16, 0, 0x11000
	v_readfirstlane_b32 s7, v27
	v_or_b32_e32 v136, s22, v22
	s_add_i32 s0, 0, 0x17a00
	v_add_u32_e32 v22, s16, v19
	v_mul_u32_u24_e32 v19, 0x210, v28
	v_and_b32_e32 v27, 0xffffffc0, v18
	v_readlane_b32 s17, v253, 16
	v_and_b32_e32 v23, 48, v18
	v_bfe_u32 v29, v18, 5, 1
	v_add3_u32 v31, s17, v19, v27
	s_cmp_eq_u32 s68, 1
	v_lshl_add_u64 v[18:19], s[12:13], 0, v[24:25]
	v_mov_b32_e32 v24, s16
	v_lshl_add_u32 v154, v21, 5, s0
	v_lshlrev_b32_e32 v26, 4, v21
	v_lshlrev_b32_e32 v30, 3, v29
	s_cselect_b64 s[0:1], -1, 0
	v_ashrrev_i32_e32 v137, 31, v136
	v_lshl_add_u64 v[140:141], s[8:9], 0, v[0:1]
	v_mad_u32_u24 v24, v28, s66, v24
	v_lshlrev_b32_e32 v25, 4, v29
	v_lshl_add_u64 v[142:143], s[10:11], 0, v[0:1]
	v_add_u32_e32 v23, s17, v23
	s_add_i32 s8, 0, 0x17c00
	v_lshlrev_b32_e32 v0, 2, v20
	v_lshl_add_u64 v[144:145], v[18:19], 0, s[94:95]
	v_mul_u32_u24_e32 v18, 0x210, v21
	v_mov_b32_e32 v92, 0
	s_mov_b32 s15, 0
	v_lshl_add_u64 v[138:139], v[136:137], 1, s[6:7]
	s_add_i32 s12, s18, 0xb480000
	v_add3_u32 v0, s8, v27, v0
	v_mov_b32_e32 v146, v134
	v_mov_b32_e32 v147, v134
	s_mov_b64 s[8:9], 0xb780000
	v_mov_b32_e32 v161, 0
	v_add_u32_e32 v155, v22, v26
	v_add_u32_e32 v156, v31, v30
	v_add_u32_e32 v157, v24, v25
	v_add_u32_e32 v158, v23, v18
	v_readlane_b32 s10, v253, 17
	v_mov_b32_e32 v162, 0
	v_mov_b32_e32 v159, 0
	v_mov_b32_e32 v160, 0
	v_mov_b32_e32 v153, 0
	v_mov_b32_e32 v152, 0
	v_mov_b32_e32 v149, 0
	v_mov_b32_e32 v148, 0
	v_mov_b32_e32 v93, v92
	v_mov_b32_e32 v90, v92
	v_mov_b32_e32 v91, v92
	v_mov_b32_e32 v20, v92
	v_mov_b32_e32 v21, v92
	v_mov_b32_e32 v18, v92
	v_mov_b32_e32 v19, v92
	s_and_b64 vcc, exec, s[0:1]
	s_cbranch_vccz .Lscan_p0
.LBB0_526:
	s_add_i32 s11, s10, -8
	s_nop 3
	v_mov_b32_e32 v26, s11
	ds_read_b128 v[22:25], v154
	ds_read_b32 v32, v26
	ds_read_b128 v[26:29], v154 offset:16
	s_waitcnt vmcnt(16)
	v_lshlrev_b32_e32 v30, 16, v126
	v_and_b32_e32 v31, 0xffff0000, v126
	s_waitcnt lgkmcnt(2)
	v_pk_mul_f32 v[22:23], v[22:23], v[30:31]
	v_lshlrev_b32_e32 v30, 16, v127
	v_and_b32_e32 v31, 0xffff0000, v127
	v_pk_mul_f32 v[24:25], v[24:25], v[30:31]
	v_cvt_pk_bf16_f32 v22, v22, v23
	v_cvt_pk_bf16_f32 v23, v24, v25
	v_lshlrev_b32_e32 v24, 16, v128
	v_and_b32_e32 v25, 0xffff0000, v128
	s_waitcnt lgkmcnt(0)
	v_pk_mul_f32 v[24:25], v[26:27], v[24:25]
	v_lshlrev_b32_e32 v26, 16, v129
	v_and_b32_e32 v27, 0xffff0000, v129
	v_pk_mul_f32 v[26:27], v[28:29], v[26:27]
	v_cvt_pk_bf16_f32 v24, v24, v25
	v_cvt_pk_bf16_f32 v25, v26, v27
	ds_write_b128 v155, v[22:25]
	v_cvt_pk_bf16_f32 v22, v2, v3
	v_cvt_pk_bf16_f32 v23, v4, v5
	v_cvt_pk_bf16_f32 v24, v6, v7
	v_cvt_pk_bf16_f32 v25, v8, v9
	ds_write2_b64 v156, v[22:23], v[24:25] offset1:2
	v_cvt_pk_bf16_f32 v22, v10, v11
	v_cvt_pk_bf16_f32 v23, v12, v13
	v_cvt_pk_bf16_f32 v24, v14, v15
	v_cvt_pk_bf16_f32 v25, v16, v17
	ds_write2_b64 v156, v[22:23], v[24:25] offset0:4 offset1:6
	v_lshlrev_b32_e32 v24, 16, v161
	v_cndmask_b32_e64 v24, 0, v24, s[0:1]
	v_add_f32_e32 v24, v92, v24
	v_lshl_add_u64 v[22:23], s[8:9], 1, v[138:139]
	v_cvt_pk_bf16_f32 v24, v24, s0
	global_store_short v[22:23], v24, off
	v_lshlrev_b32_e32 v24, 16, v162
	v_cndmask_b32_e64 v24, 0, v24, s[0:1]
	v_add_f32_e32 v24, v93, v24
	v_cvt_pk_bf16_f32 v28, v24, s0
	v_add_co_u32_e32 v24, vcc, s46, v22
	v_readfirstlane_b32 s11, v32
	s_nop 0
	v_addc_co_u32_e32 v25, vcc, 0, v23, vcc
	v_add_co_u32_e32 v26, vcc, s28, v22
	s_cmpk_gt_i32 s11, 0x3fff
	s_nop 0
	v_addc_co_u32_e32 v27, vcc, 0, v23, vcc
	global_store_short v[26:27], v28, off offset:-4096
	v_lshlrev_b32_e32 v28, 16, v159
	v_cndmask_b32_e64 v28, 0, v28, s[0:1]
	v_add_f32_e32 v28, v90, v28
	v_cvt_pk_bf16_f32 v28, v28, s0
	global_store_short v[26:27], v28, off
	v_lshlrev_b32_e32 v28, 16, v160
	v_cndmask_b32_e64 v28, 0, v28, s[0:1]
	v_add_f32_e32 v28, v91, v28
	v_cvt_pk_bf16_f32 v30, v28, s0
	v_add_co_u32_e32 v28, vcc, s87, v22
	s_cselect_b64 s[8:9], -1, 0
	s_nop 0
	v_addc_co_u32_e32 v29, vcc, 0, v23, vcc
	global_store_short v[28:29], v30, off
	v_lshlrev_b32_e32 v30, 16, v153
	v_cndmask_b32_e64 v30, 0, v30, s[0:1]
	v_add_f32_e32 v20, v20, v30
	v_cvt_pk_bf16_f32 v20, v20, s0
	global_store_short v[22:23], v20, off offset:32
	v_lshlrev_b32_e32 v20, 16, v152
	v_cndmask_b32_e64 v20, 0, v20, s[0:1]
	v_add_f32_e32 v20, v21, v20
	v_cvt_pk_bf16_f32 v20, v20, s0
	global_store_short v[24:25], v20, off offset:32
	v_lshlrev_b32_e32 v20, 16, v149
	v_cndmask_b32_e64 v20, 0, v20, s[0:1]
	v_add_f32_e32 v18, v18, v20
	s_ashr_i32 s13, s11, 31
	s_add_i32 s18, s11, 0xffffc000
	v_cvt_pk_bf16_f32 v18, v18, s0
	s_and_b64 s[16:17], s[8:9], exec
	global_store_short v[26:27], v18, off offset:32
	v_lshlrev_b32_e32 v18, 16, v148
	s_cselect_b32 s17, 0, s13
	s_cselect_b32 s16, s18, s11
	v_cndmask_b32_e64 v18, 0, v18, s[0:1]
	s_lshl_b64 s[16:17], s[16:17], 12
	v_add_f32_e32 v18, v19, v18
	s_and_b64 s[8:9], s[8:9], exec
	v_cvt_pk_bf16_f32 v18, v18, s0
	s_cselect_b32 s8, s12, 0x9480000
	global_store_short v[28:29], v18, off offset:32
	v_lshl_add_u64 v[18:19], v[138:139], 0, s[16:17]
	s_lshl_b32 s94, s8, 1
	v_lshl_add_u64 v[152:153], v[18:19], 0, s[94:95]
	v_add_co_u32_e32 v148, vcc, s46, v152
	s_add_i32 s8, s10, -4
	s_nop 0
	v_addc_co_u32_e32 v149, vcc, 0, v153, vcc
	v_add_co_u32_e32 v128, vcc, s28, v152
	s_waitcnt lgkmcnt(0)
	s_nop 0
	v_addc_co_u32_e32 v129, vcc, 0, v153, vcc
	v_add_co_u32_e32 v126, vcc, s87, v152
	s_barrier
	s_nop 0
	v_addc_co_u32_e32 v127, vcc, 0, v153, vcc
	global_load_ushort v159, v[152:153], off
	global_load_ushort v180, v[128:129], off offset:-4096
	global_load_ushort v181, v[128:129], off
	global_load_ushort v182, v[126:127], off
	global_load_ushort v183, v[152:153], off offset:32
	global_load_ushort v184, v[128:129], off offset:32
	global_load_ushort v185, v[126:127], off offset:32
	global_load_ushort v226, v[148:149], off offset:32
	v_mov_b32_e32 v227, s8
	ds_read_b32 v18, v227
	s_waitcnt lgkmcnt(0)
	v_readfirstlane_b32 s8, v18
	s_ashr_i32 s8, s8, 7
	s_ashr_i32 s9, s8, 31
	s_lshl_b64 s[16:17], s[8:9], 19
	s_lshl_b64 s[8:9], s[8:9], 17
	v_lshl_add_u64 v[18:19], s[8:9], 0, v[132:133]
	v_lshlrev_b64 v[176:177], 1, v[18:19]
	v_lshl_add_u64 v[30:31], v[140:141], 0, v[176:177]
	v_add_co_u32_e32 v34, vcc, s46, v30
	v_lshl_add_u64 v[20:21], v[144:145], 0, s[16:17]
	s_nop 0
	v_addc_co_u32_e32 v35, vcc, 0, v31, vcc
	global_load_dwordx4 v[160:163], v[20:21], off
	s_nop 0
	global_load_dwordx4 v[18:21], v[30:31], off
	global_load_dwordx4 v[22:25], v[30:31], off offset:1024
	global_load_dwordx4 v[26:29], v[30:31], off offset:2048
	s_nop 0
	global_load_dwordx4 v[30:33], v[30:31], off offset:3072
	s_nop 0
	global_load_dwordx4 v[38:41], v[34:35], off
	global_load_dwordx4 v[42:45], v[34:35], off offset:1024
	global_load_dwordx4 v[46:49], v[34:35], off offset:2048
	s_nop 0
	global_load_dwordx4 v[34:37], v[34:35], off offset:3072
	ds_read_b128 v[78:81], v157
	ds_read_b128 v[90:93], v157 offset:32
	ds_read_b128 v[94:97], v157 offset:64
	ds_read_b128 v[164:167], v157 offset:96
	ds_read_b128 v[168:171], v157 offset:128
	ds_read_b128 v[172:175], v157 offset:160
	ds_read_b128 v[202:205], v157 offset:192
	ds_read_b128 v[206:209], v157 offset:224
	v_mov_b32_e32 v135, v134
	v_pk_mul_f32 v[16:17], v[134:135], v[16:17]
	v_pk_mul_f32 v[14:15], v[134:135], v[14:15]
	v_pk_mul_f32 v[12:13], v[134:135], v[12:13]
	v_pk_mul_f32 v[10:11], v[134:135], v[10:11]
	v_pk_mul_f32 v[8:9], v[134:135], v[8:9]
	v_pk_mul_f32 v[6:7], v[134:135], v[6:7]
	v_pk_mul_f32 v[4:5], v[134:135], v[4:5]
	v_pk_mul_f32 v[2:3], v[146:147], v[2:3]
	s_waitcnt vmcnt(32) lgkmcnt(7)
	s_nop 0
	v_mfma_f32_32x32x16_bf16 v[2:17], v[102:105], v[78:81], v[2:17]
	v_lshl_add_u64 v[78:79], v[142:143], 0, v[176:177]
	s_waitcnt vmcnt(31) lgkmcnt(6)
	v_mfma_f32_32x32x16_bf16 v[2:17], v[106:109], v[90:93], v[2:17]
	s_waitcnt vmcnt(30) lgkmcnt(5)
	v_mfma_f32_32x32x16_bf16 v[2:17], v[98:101], v[94:97], v[2:17]
	s_waitcnt vmcnt(29) lgkmcnt(4)
	v_mfma_f32_32x32x16_bf16 v[2:17], v[110:113], v[164:167], v[2:17]
	global_load_dwordx4 v[110:113], v[78:79], off
	global_load_dwordx4 v[102:105], v[78:79], off offset:1024
	s_waitcnt vmcnt(30) lgkmcnt(3)
	v_mfma_f32_32x32x16_bf16 v[2:17], v[114:117], v[168:171], v[2:17]
	global_load_dwordx4 v[114:117], v[78:79], off offset:2048
	global_load_dwordx4 v[106:109], v[78:79], off offset:3072
	v_add_co_u32_e32 v78, vcc, s46, v78
	s_nop 1
	v_addc_co_u32_e32 v79, vcc, 0, v79, vcc
	global_load_dwordx4 v[98:101], v[78:79], off
	global_load_dwordx4 v[94:97], v[78:79], off offset:1024
	global_load_dwordx4 v[90:93], v[78:79], off offset:2048
	s_nop 0
	global_load_dwordx4 v[78:81], v[78:79], off offset:3072
	s_waitcnt vmcnt(35) lgkmcnt(2)
	v_mfma_f32_32x32x16_bf16 v[2:17], v[118:121], v[172:175], v[2:17]
	s_waitcnt vmcnt(34) lgkmcnt(1)
	v_mfma_f32_32x32x16_bf16 v[2:17], v[122:125], v[202:205], v[2:17]
	ds_read_b128 v[118:121], v158
	ds_read_b128 v[122:125], v158 offset:64
	ds_read_b128 v[164:167], v158 offset:128
	ds_read_b128 v[168:171], v158 offset:192
	ds_read_b128 v[172:175], v158 offset:256
	ds_read_b128 v[202:205], v158 offset:320
	ds_read_b128 v[210:213], v158 offset:384
	ds_read_b128 v[214:217], v158 offset:448
	s_waitcnt lgkmcnt(7)
	v_mfma_f32_16x16x32_bf16 v[118:121], v[50:53], v[118:121], 0
	s_waitcnt lgkmcnt(6)
	v_mfma_f32_16x16x32_bf16 v[118:121], v[54:57], v[122:125], v[118:121]
	s_waitcnt lgkmcnt(5)
	v_mfma_f32_16x16x32_bf16 v[118:121], v[58:61], v[164:167], v[118:121]
	s_waitcnt lgkmcnt(4)
	v_mfma_f32_16x16x32_bf16 v[118:121], v[62:65], v[168:171], v[118:121]
	s_waitcnt lgkmcnt(3)
	v_mfma_f32_16x16x32_bf16 v[118:121], v[66:69], v[172:175], v[118:121]
	s_waitcnt lgkmcnt(2)
	v_mfma_f32_16x16x32_bf16 v[118:121], v[70:73], v[202:205], v[118:121]
	s_waitcnt lgkmcnt(1)
	v_mfma_f32_16x16x32_bf16 v[118:121], v[74:77], v[210:213], v[118:121]
	s_waitcnt lgkmcnt(0)
	v_mfma_f32_16x16x32_bf16 v[118:121], v[82:85], v[214:217], v[118:121]
	ds_read_b128 v[122:125], v0
	ds_read_b128 v[164:167], v158 offset:8448
	ds_read_b128 v[168:171], v158 offset:8512
	ds_read_b128 v[172:175], v158 offset:8576
	ds_read_b128 v[202:205], v158 offset:8640
	ds_read_b128 v[210:213], v158 offset:8704
	ds_read_b128 v[214:217], v158 offset:8768
	ds_read_b128 v[218:221], v158 offset:8832
	ds_read_b128 v[222:225], v158 offset:8896
	s_waitcnt lgkmcnt(7)
	v_mfma_f32_16x16x32_bf16 v[50:53], v[50:53], v[164:167], 0
	s_waitcnt lgkmcnt(6)
	v_mfma_f32_16x16x32_bf16 v[50:53], v[54:57], v[168:171], v[50:53]
	ds_read_b128 v[54:57], v0
	s_waitcnt lgkmcnt(0)
	s_barrier
	v_mfma_f32_16x16x32_bf16 v[50:53], v[58:61], v[172:175], v[50:53]
	v_mfma_f32_16x16x32_bf16 v[50:53], v[62:65], v[202:205], v[50:53]
	v_mfma_f32_16x16x32_bf16 v[50:53], v[66:69], v[210:213], v[50:53]
	ds_read_b32 v68, v227
	ds_read_b128 v[58:61], v154
	ds_read_b128 v[62:65], v154 offset:16
	s_waitcnt vmcnt(16)
	v_lshlrev_b32_e32 v66, 16, v160
	v_and_b32_e32 v67, 0xffff0000, v160
	v_mfma_f32_32x32x16_bf16 v[2:17], v[86:89], v[206:209], v[2:17]
	s_waitcnt lgkmcnt(1)
	v_mul_f32_e64 v58, v58, v66
	v_mul_f32_e64 v59, v59, v67
	v_lshlrev_b32_e32 v66, 16, v161
	v_and_b32_e32 v67, 0xffff0000, v161
	v_pk_mul_f32 v[60:61], v[60:61], v[66:67]
	v_cvt_pk_bf16_f32 v58, v58, v59
	v_cvt_pk_bf16_f32 v59, v60, v61
	v_lshlrev_b32_e32 v60, 16, v162
	v_and_b32_e32 v61, 0xffff0000, v162
	s_waitcnt lgkmcnt(0)
	v_pk_mul_f32 v[60:61], v[62:63], v[60:61]
	v_lshlrev_b32_e32 v62, 16, v163
	v_and_b32_e32 v63, 0xffff0000, v163
	v_pk_mul_f32 v[62:63], v[64:65], v[62:63]
	v_cvt_pk_bf16_f32 v60, v60, v61
	v_cvt_pk_bf16_f32 v61, v62, v63
	ds_write_b128 v155, v[58:61]
	v_cvt_pk_bf16_f32 v58, v2, v3
	v_cvt_pk_bf16_f32 v59, v4, v5
	v_cvt_pk_bf16_f32 v60, v6, v7
	v_cvt_pk_bf16_f32 v61, v8, v9
	ds_write2_b64 v156, v[58:59], v[60:61] offset1:2
	v_cvt_pk_bf16_f32 v58, v10, v11
	v_cvt_pk_bf16_f32 v59, v12, v13
	v_cvt_pk_bf16_f32 v60, v14, v15
	v_cvt_pk_bf16_f32 v61, v16, v17
	ds_write2_b64 v156, v[58:59], v[60:61] offset0:4 offset1:6
	v_lshlrev_b32_e32 v58, 16, v159
	v_cndmask_b32_e64 v58, 0, v58, s[0:1]
	v_fmac_f32_e32 v58, v118, v122
	v_cvt_pk_bf16_f32 v58, v58, s0
	global_store_short v[152:153], v58, off
	v_lshlrev_b32_e32 v58, 16, v180
	v_cndmask_b32_e64 v58, 0, v58, s[0:1]
	v_mfma_f32_16x16x32_bf16 v[50:53], v[70:73], v[214:217], v[50:53]
	v_fmac_f32_e32 v58, v119, v123
	v_cvt_pk_bf16_f32 v58, v58, s0
	global_store_short v[128:129], v58, off offset:-4096
	v_lshlrev_b32_e32 v58, 16, v181
	v_cndmask_b32_e64 v58, 0, v58, s[0:1]
	v_mfma_f32_16x16x32_bf16 v[50:53], v[74:77], v[218:221], v[50:53]
	v_fmac_f32_e32 v58, v120, v124
	v_cvt_pk_bf16_f32 v58, v58, s0
	global_store_short v[128:129], v58, off
	v_lshlrev_b32_e32 v58, 16, v182
	v_cndmask_b32_e64 v58, 0, v58, s[0:1]
	v_mfma_f32_16x16x32_bf16 v[50:53], v[82:85], v[222:225], v[50:53]
	v_fmac_f32_e32 v58, v121, v125
	v_cvt_pk_bf16_f32 v58, v58, s0
	global_store_short v[126:127], v58, off
	v_lshlrev_b32_e32 v58, 16, v183
	v_cndmask_b32_e64 v58, 0, v58, s[0:1]
	s_nop 2
	v_fmac_f32_e32 v58, v50, v54
	v_cvt_pk_bf16_f32 v50, v58, s0
	global_store_short v[152:153], v50, off offset:32
	v_lshlrev_b32_e32 v50, 16, v226
	v_cndmask_b32_e64 v50, 0, v50, s[0:1]
	v_fmac_f32_e32 v50, v51, v55
	v_cvt_pk_bf16_f32 v50, v50, s0
	global_store_short v[148:149], v50, off offset:32
	v_lshlrev_b32_e32 v50, 16, v184
	v_cndmask_b32_e64 v50, 0, v50, s[0:1]
	v_readfirstlane_b32 s8, v68
	v_fmac_f32_e32 v50, v52, v56
	s_ashr_i32 s9, s8, 31
	s_add_i32 s11, s8, 0xffffc000
	v_cvt_pk_bf16_f32 v50, v50, s0
	s_cmpk_gt_i32 s8, 0x3fff
	global_store_short v[128:129], v50, off offset:32
	v_lshlrev_b32_e32 v50, 16, v185
	s_cselect_b32 s9, 0, s9
	s_cselect_b32 s8, s11, s8
	v_cndmask_b32_e64 v50, 0, v50, s[0:1]
	s_cselect_b32 s11, 0, 0
	s_cselect_b32 s13, s12, 0x9480000
	s_lshl_b64 s[8:9], s[8:9], 11
	v_fmac_f32_e32 v50, v53, v57
	s_add_u32 s8, s8, s13
	v_cvt_pk_bf16_f32 v50, v50, s0
	s_addc_u32 s9, s9, s11
	global_store_short v[126:127], v50, off offset:32
	v_lshl_add_u64 v[50:51], s[8:9], 1, v[138:139]
	v_add_co_u32_e32 v52, vcc, s46, v50
	s_waitcnt lgkmcnt(0)
	s_nop 0
	v_addc_co_u32_e32 v53, vcc, 0, v51, vcc
	v_add_co_u32_e32 v54, vcc, s28, v50
	s_barrier
	s_nop 0
	v_addc_co_u32_e32 v55, vcc, 0, v51, vcc
	v_add_co_u32_e32 v56, vcc, s87, v50
	s_nop 1
	v_addc_co_u32_e32 v57, vcc, 0, v51, vcc
	global_load_ushort v161, v[50:51], off
	global_load_ushort v162, v[54:55], off offset:-4096
	global_load_ushort v159, v[54:55], off
	global_load_ushort v160, v[56:57], off
	global_load_ushort v153, v[50:51], off offset:32
	global_load_ushort v152, v[52:53], off offset:32
	global_load_ushort v149, v[54:55], off offset:32
	global_load_ushort v148, v[56:57], off offset:32
	v_mov_b32_e32 v50, s10
	ds_read_b32 v50, v50
	s_waitcnt lgkmcnt(0)
	v_readfirstlane_b32 s11, v50
	s_ashr_i32 s16, s11, 7
	s_ashr_i32 s17, s16, 31
	s_lshl_b64 s[18:19], s[16:17], 19
	s_lshl_b64 s[16:17], s[16:17], 17
	v_lshl_add_u64 v[50:51], s[16:17], 0, v[132:133]
	v_lshlrev_b64 v[176:177], 1, v[50:51]
	v_lshl_add_u64 v[66:67], v[140:141], 0, v[176:177]
	v_add_co_u32_e32 v82, vcc, s46, v66
	v_lshl_add_u64 v[52:53], v[144:145], 0, s[18:19]
	s_nop 0
	v_addc_co_u32_e32 v83, vcc, 0, v67, vcc
	global_load_dwordx4 v[126:129], v[52:53], off
	s_nop 0
	global_load_dwordx4 v[50:53], v[66:67], off
	global_load_dwordx4 v[54:57], v[66:67], off offset:1024
	global_load_dwordx4 v[58:61], v[66:67], off offset:2048
	global_load_dwordx4 v[62:65], v[66:67], off offset:3072
	s_nop 0
	global_load_dwordx4 v[66:69], v[82:83], off
	global_load_dwordx4 v[70:73], v[82:83], off offset:1024
	global_load_dwordx4 v[74:77], v[82:83], off offset:2048
	s_nop 0
	global_load_dwordx4 v[82:85], v[82:83], off offset:3072
	ds_read_b128 v[86:89], v157
	ds_read_b128 v[118:121], v157 offset:32
	ds_read_b128 v[122:125], v157 offset:64
	ds_read_b128 v[164:167], v157 offset:96
	ds_read_b128 v[168:171], v157 offset:128
	ds_read_b128 v[172:175], v157 offset:160
	ds_read_b128 v[202:205], v157 offset:192
	ds_read_b128 v[206:209], v157 offset:224
	v_pk_mul_f32 v[16:17], v[134:135], v[16:17]
	v_pk_mul_f32 v[14:15], v[134:135], v[14:15]
	v_pk_mul_f32 v[12:13], v[134:135], v[12:13]
	v_pk_mul_f32 v[10:11], v[134:135], v[10:11]
	v_pk_mul_f32 v[8:9], v[134:135], v[8:9]
	v_pk_mul_f32 v[6:7], v[134:135], v[6:7]
	v_pk_mul_f32 v[4:5], v[134:135], v[4:5]
	v_pk_mul_f32 v[2:3], v[146:147], v[2:3]
	s_waitcnt vmcnt(32) lgkmcnt(7)
	s_nop 0
	v_mfma_f32_32x32x16_bf16 v[2:17], v[110:113], v[86:89], v[2:17]
	v_lshl_add_u64 v[86:87], v[142:143], 0, v[176:177]
	s_waitcnt vmcnt(31) lgkmcnt(6)
	v_mfma_f32_32x32x16_bf16 v[2:17], v[102:105], v[118:121], v[2:17]
	s_waitcnt vmcnt(30) lgkmcnt(5)
	v_mfma_f32_32x32x16_bf16 v[2:17], v[114:117], v[122:125], v[2:17]
	s_waitcnt vmcnt(29) lgkmcnt(4)
	v_mfma_f32_32x32x16_bf16 v[2:17], v[106:109], v[164:167], v[2:17]
	global_load_dwordx4 v[102:105], v[86:87], off
	global_load_dwordx4 v[106:109], v[86:87], off offset:1024
	s_waitcnt vmcnt(30) lgkmcnt(3)
	v_mfma_f32_32x32x16_bf16 v[2:17], v[98:101], v[168:171], v[2:17]
	global_load_dwordx4 v[98:101], v[86:87], off offset:2048
	global_load_dwordx4 v[110:113], v[86:87], off offset:3072
	v_add_co_u32_e32 v86, vcc, s46, v86
	s_nop 1
	v_addc_co_u32_e32 v87, vcc, 0, v87, vcc
	global_load_dwordx4 v[114:117], v[86:87], off
	global_load_dwordx4 v[118:121], v[86:87], off offset:1024
	global_load_dwordx4 v[122:125], v[86:87], off offset:2048
	s_nop 0
	global_load_dwordx4 v[86:89], v[86:87], off offset:3072
	s_waitcnt vmcnt(35) lgkmcnt(2)
	v_mfma_f32_32x32x16_bf16 v[2:17], v[94:97], v[172:175], v[2:17]
	s_waitcnt vmcnt(34) lgkmcnt(1)
	v_mfma_f32_32x32x16_bf16 v[2:17], v[90:93], v[202:205], v[2:17]
	ds_read_b128 v[90:93], v158
	ds_read_b128 v[94:97], v158 offset:64
	ds_read_b128 v[164:167], v158 offset:128
	ds_read_b128 v[168:171], v158 offset:192
	ds_read_b128 v[172:175], v158 offset:256
	ds_read_b128 v[202:205], v158 offset:320
	ds_read_b128 v[210:213], v158 offset:384
	ds_read_b128 v[214:217], v158 offset:448
	s_waitcnt lgkmcnt(7)
	v_mfma_f32_16x16x32_bf16 v[90:93], v[18:21], v[90:93], 0
	s_waitcnt lgkmcnt(6)
	v_mfma_f32_16x16x32_bf16 v[90:93], v[22:25], v[94:97], v[90:93]
	s_waitcnt lgkmcnt(5)
	v_mfma_f32_16x16x32_bf16 v[90:93], v[26:29], v[164:167], v[90:93]
	ds_read_b128 v[164:167], v0
	s_waitcnt lgkmcnt(5)
	v_mfma_f32_16x16x32_bf16 v[90:93], v[30:33], v[168:171], v[90:93]
	s_waitcnt lgkmcnt(4)
	v_mfma_f32_16x16x32_bf16 v[90:93], v[38:41], v[172:175], v[90:93]
	s_waitcnt lgkmcnt(3)
	v_mfma_f32_16x16x32_bf16 v[90:93], v[42:45], v[202:205], v[90:93]
	s_waitcnt lgkmcnt(2)
	v_mfma_f32_16x16x32_bf16 v[90:93], v[46:49], v[210:213], v[90:93]
	s_waitcnt lgkmcnt(1)
	v_mfma_f32_16x16x32_bf16 v[92:95], v[34:37], v[214:217], v[90:93]
	s_waitcnt lgkmcnt(0)
	s_nop 6
	v_pk_mul_f32 v[90:91], v[94:95], v[166:167]
	v_pk_mul_f32 v[92:93], v[92:93], v[164:165]
	ds_read_b128 v[94:97], v158 offset:8448
	ds_read_b128 v[164:167], v158 offset:8512
	ds_read_b128 v[168:171], v158 offset:8576
	ds_read_b128 v[172:175], v158 offset:8640
	ds_read_b128 v[202:205], v158 offset:8704
	ds_read_b128 v[210:213], v158 offset:8768
	ds_read_b128 v[214:217], v158 offset:8832
	ds_read_b128 v[218:221], v158 offset:8896
	s_waitcnt lgkmcnt(7)
	v_mfma_f32_16x16x32_bf16 v[18:21], v[18:21], v[94:97], 0
	s_add_i32 s15, s15, 2
	s_add_i32 s10, s10, 8
	s_cmp_ge_u32 s15, s14
	s_waitcnt lgkmcnt(6)
	v_mfma_f32_16x16x32_bf16 v[18:21], v[22:25], v[164:167], v[18:21]
	ds_read_b128 v[22:25], v0
	s_waitcnt lgkmcnt(0)
	s_barrier
	v_mfma_f32_16x16x32_bf16 v[18:21], v[26:29], v[168:171], v[18:21]
	v_mfma_f32_16x16x32_bf16 v[18:21], v[30:33], v[172:175], v[18:21]
	v_mfma_f32_16x16x32_bf16 v[18:21], v[38:41], v[202:205], v[18:21]
	v_mfma_f32_16x16x32_bf16 v[18:21], v[42:45], v[210:213], v[18:21]
	v_mfma_f32_16x16x32_bf16 v[18:21], v[46:49], v[214:217], v[18:21]
	s_waitcnt vmcnt(33)
	v_mfma_f32_32x32x16_bf16 v[2:17], v[78:81], v[206:209], v[2:17]
	v_mfma_f32_16x16x32_bf16 v[26:29], v[34:37], v[218:221], v[18:21]
	s_nop 7
	v_pk_mul_f32 v[18:19], v[28:29], v[24:25]
	v_pk_mul_f32 v[20:21], v[26:27], v[22:23]
	s_cbranch_scc0 .LBB0_526
	s_branch .Lscan_x
.Lscan_p0:
	s_add_i32 s11, s10, -8
	s_nop 3
	v_mov_b32_e32 v26, s11
	ds_read_b128 v[22:25], v154
	ds_read_b32 v32, v26
	ds_read_b128 v[26:29], v154 offset:16
	s_waitcnt vmcnt(16)
	v_lshlrev_b32_e32 v30, 16, v126
	v_and_b32_e32 v31, 0xffff0000, v126
	s_waitcnt lgkmcnt(2)
	v_pk_mul_f32 v[22:23], v[22:23], v[30:31]
	v_lshlrev_b32_e32 v30, 16, v127
	v_and_b32_e32 v31, 0xffff0000, v127
	v_pk_mul_f32 v[24:25], v[24:25], v[30:31]
	v_cvt_pk_bf16_f32 v22, v22, v23
	v_cvt_pk_bf16_f32 v23, v24, v25
	v_lshlrev_b32_e32 v24, 16, v128
	v_and_b32_e32 v25, 0xffff0000, v128
	s_waitcnt lgkmcnt(0)
	v_pk_mul_f32 v[24:25], v[26:27], v[24:25]
	v_lshlrev_b32_e32 v26, 16, v129
	v_and_b32_e32 v27, 0xffff0000, v129
	v_pk_mul_f32 v[26:27], v[28:29], v[26:27]
	v_cvt_pk_bf16_f32 v24, v24, v25
	v_cvt_pk_bf16_f32 v25, v26, v27
	ds_write_b128 v155, v[22:25]
	v_cvt_pk_bf16_f32 v22, v2, v3
	v_cvt_pk_bf16_f32 v23, v4, v5
	v_cvt_pk_bf16_f32 v24, v6, v7
	v_cvt_pk_bf16_f32 v25, v8, v9
	ds_write2_b64 v156, v[22:23], v[24:25] offset1:2
	v_cvt_pk_bf16_f32 v22, v10, v11
	v_cvt_pk_bf16_f32 v23, v12, v13
	v_cvt_pk_bf16_f32 v24, v14, v15
	v_cvt_pk_bf16_f32 v25, v16, v17
	ds_write2_b64 v156, v[22:23], v[24:25] offset0:4 offset1:6
	v_mov_b32_e32 v24, v92
	v_lshl_add_u64 v[22:23], s[8:9], 1, v[138:139]
	v_cvt_pk_bf16_f32 v24, v24, s0
	global_store_short v[22:23], v24, off
	v_mov_b32_e32 v24, v93
	v_cvt_pk_bf16_f32 v28, v24, s0
	v_add_co_u32_e32 v24, vcc, s46, v22
	v_readfirstlane_b32 s11, v32
	s_nop 0
	v_addc_co_u32_e32 v25, vcc, 0, v23, vcc
	v_add_co_u32_e32 v26, vcc, s28, v22
	s_cmpk_gt_i32 s11, 0x3fff
	s_nop 0
	v_addc_co_u32_e32 v27, vcc, 0, v23, vcc
	global_store_short v[26:27], v28, off offset:-4096
	v_mov_b32_e32 v28, v90
	v_cvt_pk_bf16_f32 v28, v28, s0
	global_store_short v[26:27], v28, off
	v_mov_b32_e32 v28, v91
	v_cvt_pk_bf16_f32 v30, v28, s0
	v_add_co_u32_e32 v28, vcc, s87, v22
	s_cselect_b64 s[8:9], -1, 0
	s_nop 0
	v_addc_co_u32_e32 v29, vcc, 0, v23, vcc
	global_store_short v[28:29], v30, off
	v_cvt_pk_bf16_f32 v20, v20, s0
	global_store_short v[22:23], v20, off offset:32
	v_mov_b32_e32 v20, v21
	v_cvt_pk_bf16_f32 v20, v20, s0
	global_store_short v[24:25], v20, off offset:32
	s_ashr_i32 s13, s11, 31
	s_add_i32 s18, s11, 0xffffc000
	v_cvt_pk_bf16_f32 v18, v18, s0
	s_and_b64 s[16:17], s[8:9], exec
	global_store_short v[26:27], v18, off offset:32
	s_cselect_b32 s17, 0, s13
	s_cselect_b32 s16, s18, s11
	s_lshl_b64 s[16:17], s[16:17], 12
	v_mov_b32_e32 v18, v19
	s_and_b64 s[8:9], s[8:9], exec
	v_cvt_pk_bf16_f32 v18, v18, s0
	s_cselect_b32 s8, s12, 0x9480000
	global_store_short v[28:29], v18, off offset:32
	v_lshl_add_u64 v[18:19], v[138:139], 0, s[16:17]
	s_lshl_b32 s94, s8, 1
	v_lshl_add_u64 v[152:153], v[18:19], 0, s[94:95]
	v_add_co_u32_e32 v148, vcc, s46, v152
	s_add_i32 s8, s10, -4
	s_nop 0
	v_addc_co_u32_e32 v149, vcc, 0, v153, vcc
	v_add_co_u32_e32 v128, vcc, s28, v152
	s_waitcnt lgkmcnt(0)
	s_nop 0
	v_addc_co_u32_e32 v129, vcc, 0, v153, vcc
	v_add_co_u32_e32 v126, vcc, s87, v152
	s_barrier
	s_nop 0
	v_addc_co_u32_e32 v127, vcc, 0, v153, vcc
	v_mov_b32_e32 v227, s8
	ds_read_b32 v18, v227
	s_waitcnt lgkmcnt(0)
	v_readfirstlane_b32 s8, v18
	s_ashr_i32 s8, s8, 7
	s_ashr_i32 s9, s8, 31
	s_lshl_b64 s[16:17], s[8:9], 19
	s_lshl_b64 s[8:9], s[8:9], 17
	v_lshl_add_u64 v[18:19], s[8:9], 0, v[132:133]
	v_lshlrev_b64 v[176:177], 1, v[18:19]
	v_lshl_add_u64 v[30:31], v[140:141], 0, v[176:177]
	v_add_co_u32_e32 v34, vcc, s46, v30
	v_lshl_add_u64 v[20:21], v[144:145], 0, s[16:17]
	s_nop 0
	v_addc_co_u32_e32 v35, vcc, 0, v31, vcc
	global_load_dwordx4 v[160:163], v[20:21], off
	s_nop 0
	global_load_dwordx4 v[18:21], v[30:31], off
	global_load_dwordx4 v[22:25], v[30:31], off offset:1024
	global_load_dwordx4 v[26:29], v[30:31], off offset:2048
	s_nop 0
	global_load_dwordx4 v[30:33], v[30:31], off offset:3072
	s_nop 0
	global_load_dwordx4 v[38:41], v[34:35], off
	global_load_dwordx4 v[42:45], v[34:35], off offset:1024
	global_load_dwordx4 v[46:49], v[34:35], off offset:2048
	s_nop 0
	global_load_dwordx4 v[34:37], v[34:35], off offset:3072
	ds_read_b128 v[78:81], v157
	ds_read_b128 v[90:93], v157 offset:32
	ds_read_b128 v[94:97], v157 offset:64
	ds_read_b128 v[164:167], v157 offset:96
	ds_read_b128 v[168:171], v157 offset:128
	ds_read_b128 v[172:175], v157 offset:160
	ds_read_b128 v[202:205], v157 offset:192
	ds_read_b128 v[206:209], v157 offset:224
	v_mov_b32_e32 v135, v134
	v_pk_mul_f32 v[16:17], v[134:135], v[16:17]
	v_pk_mul_f32 v[14:15], v[134:135], v[14:15]
	v_pk_mul_f32 v[12:13], v[134:135], v[12:13]
	v_pk_mul_f32 v[10:11], v[134:135], v[10:11]
	v_pk_mul_f32 v[8:9], v[134:135], v[8:9]
	v_pk_mul_f32 v[6:7], v[134:135], v[6:7]
	v_pk_mul_f32 v[4:5], v[134:135], v[4:5]
	v_pk_mul_f32 v[2:3], v[146:147], v[2:3]
	s_waitcnt vmcnt(24) lgkmcnt(7)
	s_nop 0
	v_mfma_f32_32x32x16_bf16 v[2:17], v[102:105], v[78:81], v[2:17]
	v_lshl_add_u64 v[78:79], v[142:143], 0, v[176:177]
	s_waitcnt vmcnt(23) lgkmcnt(6)
	v_mfma_f32_32x32x16_bf16 v[2:17], v[106:109], v[90:93], v[2:17]
	s_waitcnt vmcnt(22) lgkmcnt(5)
	v_mfma_f32_32x32x16_bf16 v[2:17], v[98:101], v[94:97], v[2:17]
	s_waitcnt vmcnt(21) lgkmcnt(4)
	v_mfma_f32_32x32x16_bf16 v[2:17], v[110:113], v[164:167], v[2:17]
	global_load_dwordx4 v[110:113], v[78:79], off
	global_load_dwordx4 v[102:105], v[78:79], off offset:1024
	s_waitcnt vmcnt(22) lgkmcnt(3)
	v_mfma_f32_32x32x16_bf16 v[2:17], v[114:117], v[168:171], v[2:17]
	global_load_dwordx4 v[114:117], v[78:79], off offset:2048
	global_load_dwordx4 v[106:109], v[78:79], off offset:3072
	v_add_co_u32_e32 v78, vcc, s46, v78
	s_nop 1
	v_addc_co_u32_e32 v79, vcc, 0, v79, vcc
	global_load_dwordx4 v[98:101], v[78:79], off
	global_load_dwordx4 v[94:97], v[78:79], off offset:1024
	global_load_dwordx4 v[90:93], v[78:79], off offset:2048
	s_nop 0
	global_load_dwordx4 v[78:81], v[78:79], off offset:3072
	s_waitcnt vmcnt(27) lgkmcnt(2)
	v_mfma_f32_32x32x16_bf16 v[2:17], v[118:121], v[172:175], v[2:17]
	s_waitcnt vmcnt(26) lgkmcnt(1)
	v_mfma_f32_32x32x16_bf16 v[2:17], v[122:125], v[202:205], v[2:17]
	ds_read_b128 v[118:121], v158
	ds_read_b128 v[122:125], v158 offset:64
	ds_read_b128 v[164:167], v158 offset:128
	ds_read_b128 v[168:171], v158 offset:192
	ds_read_b128 v[172:175], v158 offset:256
	ds_read_b128 v[202:205], v158 offset:320
	ds_read_b128 v[210:213], v158 offset:384
	ds_read_b128 v[214:217], v158 offset:448
	s_waitcnt lgkmcnt(7)
	v_mfma_f32_16x16x32_bf16 v[118:121], v[50:53], v[118:121], 0
	s_waitcnt lgkmcnt(6)
	v_mfma_f32_16x16x32_bf16 v[118:121], v[54:57], v[122:125], v[118:121]
	s_waitcnt lgkmcnt(5)
	v_mfma_f32_16x16x32_bf16 v[118:121], v[58:61], v[164:167], v[118:121]
	s_waitcnt lgkmcnt(4)
	v_mfma_f32_16x16x32_bf16 v[118:121], v[62:65], v[168:171], v[118:121]
	s_waitcnt lgkmcnt(3)
	v_mfma_f32_16x16x32_bf16 v[118:121], v[66:69], v[172:175], v[118:121]
	s_waitcnt lgkmcnt(2)
	v_mfma_f32_16x16x32_bf16 v[118:121], v[70:73], v[202:205], v[118:121]
	s_waitcnt lgkmcnt(1)
	v_mfma_f32_16x16x32_bf16 v[118:121], v[74:77], v[210:213], v[118:121]
	s_waitcnt lgkmcnt(0)
	v_mfma_f32_16x16x32_bf16 v[118:121], v[82:85], v[214:217], v[118:121]
	ds_read_b128 v[122:125], v0
	ds_read_b128 v[164:167], v158 offset:8448
	ds_read_b128 v[168:171], v158 offset:8512
	ds_read_b128 v[172:175], v158 offset:8576
	ds_read_b128 v[202:205], v158 offset:8640
	ds_read_b128 v[210:213], v158 offset:8704
	ds_read_b128 v[214:217], v158 offset:8768
	ds_read_b128 v[218:221], v158 offset:8832
	ds_read_b128 v[222:225], v158 offset:8896
	s_waitcnt lgkmcnt(7)
	v_mfma_f32_16x16x32_bf16 v[50:53], v[50:53], v[164:167], 0
	s_waitcnt lgkmcnt(6)
	v_mfma_f32_16x16x32_bf16 v[50:53], v[54:57], v[168:171], v[50:53]
	ds_read_b128 v[54:57], v0
	s_waitcnt lgkmcnt(0)
	s_barrier
	v_mfma_f32_16x16x32_bf16 v[50:53], v[58:61], v[172:175], v[50:53]
	v_mfma_f32_16x16x32_bf16 v[50:53], v[62:65], v[202:205], v[50:53]
	v_mfma_f32_16x16x32_bf16 v[50:53], v[66:69], v[210:213], v[50:53]
	ds_read_b32 v68, v227
	ds_read_b128 v[58:61], v154
	ds_read_b128 v[62:65], v154 offset:16
	s_waitcnt vmcnt(16)
	v_lshlrev_b32_e32 v66, 16, v160
	v_and_b32_e32 v67, 0xffff0000, v160
	v_mfma_f32_32x32x16_bf16 v[2:17], v[86:89], v[206:209], v[2:17]
	s_waitcnt lgkmcnt(1)
	v_mul_f32_e64 v58, v58, v66
	v_mul_f32_e64 v59, v59, v67
	v_lshlrev_b32_e32 v66, 16, v161
	v_and_b32_e32 v67, 0xffff0000, v161
	v_pk_mul_f32 v[60:61], v[60:61], v[66:67]
	v_cvt_pk_bf16_f32 v58, v58, v59
	v_cvt_pk_bf16_f32 v59, v60, v61
	v_lshlrev_b32_e32 v60, 16, v162
	v_and_b32_e32 v61, 0xffff0000, v162
	s_waitcnt lgkmcnt(0)
	v_pk_mul_f32 v[60:61], v[62:63], v[60:61]
	v_lshlrev_b32_e32 v62, 16, v163
	v_and_b32_e32 v63, 0xffff0000, v163
	v_pk_mul_f32 v[62:63], v[64:65], v[62:63]
	v_cvt_pk_bf16_f32 v60, v60, v61
	v_cvt_pk_bf16_f32 v61, v62, v63
	ds_write_b128 v155, v[58:61]
	v_cvt_pk_bf16_f32 v58, v2, v3
	v_cvt_pk_bf16_f32 v59, v4, v5
	v_cvt_pk_bf16_f32 v60, v6, v7
	v_cvt_pk_bf16_f32 v61, v8, v9
	ds_write2_b64 v156, v[58:59], v[60:61] offset1:2
	v_cvt_pk_bf16_f32 v58, v10, v11
	v_cvt_pk_bf16_f32 v59, v12, v13
	v_cvt_pk_bf16_f32 v60, v14, v15
	v_cvt_pk_bf16_f32 v61, v16, v17
	ds_write2_b64 v156, v[58:59], v[60:61] offset0:4 offset1:6
	v_mul_f32_e32 v58, v118, v122
	v_cvt_pk_bf16_f32 v58, v58, s0
	global_store_short v[152:153], v58, off
	v_mfma_f32_16x16x32_bf16 v[50:53], v[70:73], v[214:217], v[50:53]
	v_mul_f32_e32 v58, v119, v123
	v_cvt_pk_bf16_f32 v58, v58, s0
	global_store_short v[128:129], v58, off offset:-4096
	v_mfma_f32_16x16x32_bf16 v[50:53], v[74:77], v[218:221], v[50:53]
	v_mul_f32_e32 v58, v120, v124
	v_cvt_pk_bf16_f32 v58, v58, s0
	global_store_short v[128:129], v58, off
	v_mfma_f32_16x16x32_bf16 v[50:53], v[82:85], v[222:225], v[50:53]
	v_mul_f32_e32 v58, v121, v125
	v_cvt_pk_bf16_f32 v58, v58, s0
	global_store_short v[126:127], v58, off
	s_nop 2
	s_nop 1
	v_mul_f32_e32 v58, v50, v54
	v_cvt_pk_bf16_f32 v50, v58, s0
	global_store_short v[152:153], v50, off offset:32
	s_nop 3
	v_mul_f32_e32 v50, v51, v55
	v_cvt_pk_bf16_f32 v50, v50, s0
	global_store_short v[148:149], v50, off offset:32
	v_readfirstlane_b32 s8, v68
	s_nop 5
	v_mul_f32_e32 v50, v52, v56
	s_ashr_i32 s9, s8, 31
	s_add_i32 s11, s8, 0xffffc000
	v_cvt_pk_bf16_f32 v50, v50, s0
	s_cmpk_gt_i32 s8, 0x3fff
	global_store_short v[128:129], v50, off offset:32
	s_cselect_b32 s9, 0, s9
	s_cselect_b32 s8, s11, s8
	s_cselect_b32 s11, 0, 0
	s_cselect_b32 s13, s12, 0x9480000
	s_lshl_b64 s[8:9], s[8:9], 11
	v_mul_f32_e32 v50, v53, v57
	s_add_u32 s8, s8, s13
	v_cvt_pk_bf16_f32 v50, v50, s0
	s_addc_u32 s9, s9, s11
	global_store_short v[126:127], v50, off offset:32
	v_lshl_add_u64 v[50:51], s[8:9], 1, v[138:139]
	v_add_co_u32_e32 v52, vcc, s46, v50
	s_waitcnt lgkmcnt(0)
	s_nop 0
	v_addc_co_u32_e32 v53, vcc, 0, v51, vcc
	v_add_co_u32_e32 v54, vcc, s28, v50
	s_barrier
	s_nop 0
	v_addc_co_u32_e32 v55, vcc, 0, v51, vcc
	v_add_co_u32_e32 v56, vcc, s87, v50
	s_nop 1
	v_addc_co_u32_e32 v57, vcc, 0, v51, vcc
	v_mov_b32_e32 v50, s10
	ds_read_b32 v50, v50
	s_waitcnt lgkmcnt(0)
	v_readfirstlane_b32 s11, v50
	s_ashr_i32 s16, s11, 7
	s_ashr_i32 s17, s16, 31
	s_lshl_b64 s[18:19], s[16:17], 19
	s_lshl_b64 s[16:17], s[16:17], 17
	v_lshl_add_u64 v[50:51], s[16:17], 0, v[132:133]
	v_lshlrev_b64 v[176:177], 1, v[50:51]
	v_lshl_add_u64 v[66:67], v[140:141], 0, v[176:177]
	v_add_co_u32_e32 v82, vcc, s46, v66
	v_lshl_add_u64 v[52:53], v[144:145], 0, s[18:19]
	s_nop 0
	v_addc_co_u32_e32 v83, vcc, 0, v67, vcc
	global_load_dwordx4 v[126:129], v[52:53], off
	s_nop 0
	global_load_dwordx4 v[50:53], v[66:67], off
	global_load_dwordx4 v[54:57], v[66:67], off offset:1024
	global_load_dwordx4 v[58:61], v[66:67], off offset:2048
	global_load_dwordx4 v[62:65], v[66:67], off offset:3072
	s_nop 0
	global_load_dwordx4 v[66:69], v[82:83], off
	global_load_dwordx4 v[70:73], v[82:83], off offset:1024
	global_load_dwordx4 v[74:77], v[82:83], off offset:2048
	s_nop 0
	global_load_dwordx4 v[82:85], v[82:83], off offset:3072
	ds_read_b128 v[86:89], v157
	ds_read_b128 v[118:121], v157 offset:32
	ds_read_b128 v[122:125], v157 offset:64
	ds_read_b128 v[164:167], v157 offset:96
	ds_read_b128 v[168:171], v157 offset:128
	ds_read_b128 v[172:175], v157 offset:160
	ds_read_b128 v[202:205], v157 offset:192
	ds_read_b128 v[206:209], v157 offset:224
	v_pk_mul_f32 v[16:17], v[134:135], v[16:17]
	v_pk_mul_f32 v[14:15], v[134:135], v[14:15]
	v_pk_mul_f32 v[12:13], v[134:135], v[12:13]
	v_pk_mul_f32 v[10:11], v[134:135], v[10:11]
	v_pk_mul_f32 v[8:9], v[134:135], v[8:9]
	v_pk_mul_f32 v[6:7], v[134:135], v[6:7]
	v_pk_mul_f32 v[4:5], v[134:135], v[4:5]
	v_pk_mul_f32 v[2:3], v[146:147], v[2:3]
	s_waitcnt vmcnt(24) lgkmcnt(7)
	s_nop 0
	v_mfma_f32_32x32x16_bf16 v[2:17], v[110:113], v[86:89], v[2:17]
	v_lshl_add_u64 v[86:87], v[142:143], 0, v[176:177]
	s_waitcnt vmcnt(23) lgkmcnt(6)
	v_mfma_f32_32x32x16_bf16 v[2:17], v[102:105], v[118:121], v[2:17]
	s_waitcnt vmcnt(22) lgkmcnt(5)
	v_mfma_f32_32x32x16_bf16 v[2:17], v[114:117], v[122:125], v[2:17]
	s_waitcnt vmcnt(21) lgkmcnt(4)
	v_mfma_f32_32x32x16_bf16 v[2:17], v[106:109], v[164:167], v[2:17]
	global_load_dwordx4 v[102:105], v[86:87], off
	global_load_dwordx4 v[106:109], v[86:87], off offset:1024
	s_waitcnt vmcnt(22) lgkmcnt(3)
	v_mfma_f32_32x32x16_bf16 v[2:17], v[98:101], v[168:171], v[2:17]
	global_load_dwordx4 v[98:101], v[86:87], off offset:2048
	global_load_dwordx4 v[110:113], v[86:87], off offset:3072
	v_add_co_u32_e32 v86, vcc, s46, v86
	s_nop 1
	v_addc_co_u32_e32 v87, vcc, 0, v87, vcc
	global_load_dwordx4 v[114:117], v[86:87], off
	global_load_dwordx4 v[118:121], v[86:87], off offset:1024
	global_load_dwordx4 v[122:125], v[86:87], off offset:2048
	s_nop 0
	global_load_dwordx4 v[86:89], v[86:87], off offset:3072
	s_waitcnt vmcnt(27) lgkmcnt(2)
	v_mfma_f32_32x32x16_bf16 v[2:17], v[94:97], v[172:175], v[2:17]
	s_waitcnt vmcnt(26) lgkmcnt(1)
	v_mfma_f32_32x32x16_bf16 v[2:17], v[90:93], v[202:205], v[2:17]
	ds_read_b128 v[90:93], v158
	ds_read_b128 v[94:97], v158 offset:64
	ds_read_b128 v[164:167], v158 offset:128
	ds_read_b128 v[168:171], v158 offset:192
	ds_read_b128 v[172:175], v158 offset:256
	ds_read_b128 v[202:205], v158 offset:320
	ds_read_b128 v[210:213], v158 offset:384
	ds_read_b128 v[214:217], v158 offset:448
	s_waitcnt lgkmcnt(7)
	v_mfma_f32_16x16x32_bf16 v[90:93], v[18:21], v[90:93], 0
	s_waitcnt lgkmcnt(6)
	v_mfma_f32_16x16x32_bf16 v[90:93], v[22:25], v[94:97], v[90:93]
	s_waitcnt lgkmcnt(5)
	v_mfma_f32_16x16x32_bf16 v[90:93], v[26:29], v[164:167], v[90:93]
	ds_read_b128 v[164:167], v0
	s_waitcnt lgkmcnt(5)
	v_mfma_f32_16x16x32_bf16 v[90:93], v[30:33], v[168:171], v[90:93]
	s_waitcnt lgkmcnt(4)
	v_mfma_f32_16x16x32_bf16 v[90:93], v[38:41], v[172:175], v[90:93]
	s_waitcnt lgkmcnt(3)
	v_mfma_f32_16x16x32_bf16 v[90:93], v[42:45], v[202:205], v[90:93]
	s_waitcnt lgkmcnt(2)
	v_mfma_f32_16x16x32_bf16 v[90:93], v[46:49], v[210:213], v[90:93]
	s_waitcnt lgkmcnt(1)
	v_mfma_f32_16x16x32_bf16 v[92:95], v[34:37], v[214:217], v[90:93]
	s_waitcnt lgkmcnt(0)
	s_nop 6
	v_pk_mul_f32 v[90:91], v[94:95], v[166:167]
	v_pk_mul_f32 v[92:93], v[92:93], v[164:165]
	ds_read_b128 v[94:97], v158 offset:8448
	ds_read_b128 v[164:167], v158 offset:8512
	ds_read_b128 v[168:171], v158 offset:8576
	ds_read_b128 v[172:175], v158 offset:8640
	ds_read_b128 v[202:205], v158 offset:8704
	ds_read_b128 v[210:213], v158 offset:8768
	ds_read_b128 v[214:217], v158 offset:8832
	ds_read_b128 v[218:221], v158 offset:8896
	s_waitcnt lgkmcnt(7)
	v_mfma_f32_16x16x32_bf16 v[18:21], v[18:21], v[94:97], 0
	s_add_i32 s15, s15, 2
	s_add_i32 s10, s10, 8
	s_cmp_ge_u32 s15, s14
	s_waitcnt lgkmcnt(6)
	v_mfma_f32_16x16x32_bf16 v[18:21], v[22:25], v[164:167], v[18:21]
	ds_read_b128 v[22:25], v0
	s_waitcnt lgkmcnt(0)
	s_barrier
	v_mfma_f32_16x16x32_bf16 v[18:21], v[26:29], v[168:171], v[18:21]
	v_mfma_f32_16x16x32_bf16 v[18:21], v[30:33], v[172:175], v[18:21]
	v_mfma_f32_16x16x32_bf16 v[18:21], v[38:41], v[202:205], v[18:21]
	v_mfma_f32_16x16x32_bf16 v[18:21], v[42:45], v[210:213], v[18:21]
	v_mfma_f32_16x16x32_bf16 v[18:21], v[46:49], v[214:217], v[18:21]
	s_waitcnt vmcnt(25)
	v_mfma_f32_32x32x16_bf16 v[2:17], v[78:81], v[206:209], v[2:17]
	v_mfma_f32_16x16x32_bf16 v[26:29], v[34:37], v[218:221], v[18:21]
	s_nop 7
	v_pk_mul_f32 v[18:19], v[28:29], v[24:25]
	v_pk_mul_f32 v[20:21], v[26:27], v[22:23]
	s_cbranch_scc0 .Lscan_p0
	s_branch .Lscan_x
.Lscan_x:
	s_lshl_b64 s[8:9], s[8:9], 1
	s_waitcnt vmcnt(24)
	v_lshlrev_b32_e32 v0, 16, v161
	s_add_u32 s6, s6, s8
	v_cndmask_b32_e64 v0, 0, v0, s[0:1]
	s_addc_u32 s7, s7, s9
	v_add_f32_e32 v0, v0, v92
	v_lshl_add_u64 v[22:23], v[136:137], 1, s[6:7]
	v_cvt_pk_bf16_f32 v0, v0, s0
	global_store_short v[22:23], v0, off
	s_waitcnt vmcnt(24)
	v_lshlrev_b32_e32 v0, 16, v162
	v_add_co_u32_e32 v24, vcc, s46, v22
	v_cndmask_b32_e64 v0, 0, v0, s[0:1]
	s_nop 0
	v_addc_co_u32_e32 v25, vcc, 0, v23, vcc
	v_add_f32_e32 v0, v0, v93
	v_add_co_u32_e32 v26, vcc, s28, v22
	v_cvt_pk_bf16_f32 v0, v0, s0
	s_nop 0
	v_addc_co_u32_e32 v27, vcc, 0, v23, vcc
	global_store_short v[26:27], v0, off offset:-4096
	s_waitcnt vmcnt(24)
	v_lshlrev_b32_e32 v0, 16, v159
	v_cndmask_b32_e64 v0, 0, v0, s[0:1]
	v_add_f32_e32 v0, v0, v90
	v_cvt_pk_bf16_f32 v0, v0, s0
	global_store_short v[26:27], v0, off
	s_waitcnt vmcnt(24)
	v_lshlrev_b32_e32 v0, 16, v160
	v_cndmask_b32_e64 v0, 0, v0, s[0:1]
	v_add_f32_e32 v0, v0, v91
	v_add_co_u32_e32 v28, vcc, s87, v22
	v_cvt_pk_bf16_f32 v0, v0, s0
	s_nop 0
	v_addc_co_u32_e32 v29, vcc, 0, v23, vcc
	global_store_short v[28:29], v0, off
	s_waitcnt vmcnt(24)
	v_lshlrev_b32_e32 v0, 16, v153
	v_cndmask_b32_e64 v0, 0, v0, s[0:1]
	v_add_f32_e32 v0, v0, v20
	v_cvt_pk_bf16_f32 v0, v0, s0
	global_store_short v[22:23], v0, off offset:32
	s_waitcnt vmcnt(24)
	v_lshlrev_b32_e32 v0, 16, v152
	v_cndmask_b32_e64 v0, 0, v0, s[0:1]
	v_add_f32_e32 v0, v0, v21
	v_cvt_pk_bf16_f32 v0, v0, s0
	global_store_short v[24:25], v0, off offset:32
	s_waitcnt vmcnt(24)
	v_lshlrev_b32_e32 v0, 16, v149
	v_cndmask_b32_e64 v0, 0, v0, s[0:1]
	v_add_f32_e32 v0, v0, v18
	v_cvt_pk_bf16_f32 v0, v0, s0
	global_store_short v[26:27], v0, off offset:32
	s_waitcnt vmcnt(24)
	v_lshlrev_b32_e32 v0, 16, v148
	v_cndmask_b32_e64 v0, 0, v0, s[0:1]
	v_add_f32_e32 v0, v0, v19
	v_cvt_pk_bf16_f32 v0, v0, s0
	s_and_b64 vcc, exec, s[4:5]
	global_store_short v[28:29], v0, off offset:32
	s_cbranch_vccz .LBB0_529
	global_store_dwordx4 v[130:131], v[2:5], off
	global_store_dwordx4 v[130:131], v[6:9], off offset:16
	global_store_dwordx4 v[130:131], v[10:13], off offset:32
	global_store_dwordx4 v[130:131], v[14:17], off offset:48
